# fetch-phase pin: all code after phase 0 shifted by 8 bytes (on hand-written phase 0 + gate load hoist)
# speedup vs baseline: 1.0092x; 1.0067x over previous
; #define INP(i) ldin(i)
; #define SEAM(k) do { if (IN(k) && IN((k) + 1)) xcd_barrier(bar); } while (0)
; __global__ void __launch_bounds__(NWAVES * 64, 2) mk_fwd(Args args) {
;     ...
;     if (IN(0)) { p0_prologue(F, INP(0), WSP(bf16, WS_HB), ROWSS(0)); } SEAM(0);
.Lp0_xdone:
	s_nop 0
	s_nop 0
	s_branch .LBB0_126
